# MLA: younger wave half keeps priority 1 in its softmax segment
# baseline (speedup 1.0000x reference)
.Lmla_nowrite_B0:
	s_waitcnt lgkmcnt(9)
	v_mfma_f32_32x32x16_bf16 v[64:79], v[178:181], v[100:103], v[64:79]
	s_waitcnt lgkmcnt(8)
	v_mfma_f32_32x32x16_bf16 v[48:63], v[198:201], v[100:103], v[48:63]
	s_setprio 1
	s_waitcnt lgkmcnt(0)
	s_barrier
	s_mov_b32 s28, 1
	s_cmp_lt_i32 s28, s22
	s_cbranch_scc0 .Lmla_B_tail

.Lmla_nowrite_B:
	s_waitcnt lgkmcnt(9)
	v_mfma_f32_32x32x16_bf16 v[64:79], v[178:181], v[100:103], v[64:79]
	s_waitcnt lgkmcnt(8)
	v_mfma_f32_32x32x16_bf16 v[48:63], v[198:201], v[100:103], v[48:63]
	s_setprio 1
	s_waitcnt lgkmcnt(0)
	s_barrier
	s_add_i32 s28, s28, 1
	s_cmp_lt_i32 s28, s22
	s_cbranch_scc1 .Lmla_B_loop

.Lmla_norescale_Bt:
	v_exp_f32_e32 v64, v64
	v_exp_f32_e32 v65, v65
	v_exp_f32_e32 v66, v66
	v_exp_f32_e32 v67, v67
	v_exp_f32_e32 v68, v68
	v_exp_f32_e32 v69, v69
	v_exp_f32_e32 v70, v70
	v_exp_f32_e32 v71, v71
	v_cvt_pk_bf16_f32 v234, v64, v65
	v_cvt_pk_bf16_f32 v235, v66, v67
	v_cvt_pk_bf16_f32 v236, v68, v69
	v_cvt_pk_bf16_f32 v237, v70, v71
	v_exp_f32_e32 v72, v72
	v_exp_f32_e32 v73, v73
	v_exp_f32_e32 v74, v74
	v_exp_f32_e32 v75, v75
	v_exp_f32_e32 v76, v76
	v_exp_f32_e32 v77, v77
	v_exp_f32_e32 v78, v78
	v_exp_f32_e32 v79, v79
	v_cvt_pk_bf16_f32 v238, v72, v73
	v_cvt_pk_bf16_f32 v239, v74, v75
	v_cvt_pk_bf16_f32 v240, v76, v77
	v_cvt_pk_bf16_f32 v241, v78, v79
	v_exp_f32_e32 v48, v48
	v_exp_f32_e32 v49, v49
	v_exp_f32_e32 v50, v50
	v_exp_f32_e32 v51, v51
	v_exp_f32_e32 v52, v52
	v_exp_f32_e32 v53, v53
	v_exp_f32_e32 v54, v54
	v_exp_f32_e32 v55, v55
	v_cvt_pk_bf16_f32 v242, v48, v49
	v_cvt_pk_bf16_f32 v243, v50, v51
	v_cvt_pk_bf16_f32 v244, v52, v53
	v_cvt_pk_bf16_f32 v245, v54, v55
	v_exp_f32_e32 v56, v56
	v_exp_f32_e32 v57, v57
	v_exp_f32_e32 v58, v58
	v_exp_f32_e32 v59, v59
	v_exp_f32_e32 v60, v60
	v_exp_f32_e32 v61, v61
	v_exp_f32_e32 v62, v62
	v_exp_f32_e32 v63, v63
	v_cvt_pk_bf16_f32 v246, v56, v57
	v_cvt_pk_bf16_f32 v247, v58, v59
	v_cvt_pk_bf16_f32 v248, v60, v61
	v_cvt_pk_bf16_f32 v249, v62, v63
	v_add_f32_e32 v172, v64, v65
	v_add_f32_e32 v173, v66, v67
	v_add_f32_e32 v177, v68, v69
	v_add_f32_e32 v64, v70, v71
	v_add_f32_e32 v172, v172, v72
	v_add_f32_e32 v173, v173, v73
	v_add_f32_e32 v177, v177, v74
	v_add_f32_e32 v64, v64, v75
	v_add_f32_e32 v172, v172, v76
	v_add_f32_e32 v173, v173, v77
	v_add_f32_e32 v177, v177, v78
	v_add_f32_e32 v64, v64, v79
	v_add_f32_e32 v172, v172, v48
	v_add_f32_e32 v173, v173, v49
	v_add_f32_e32 v177, v177, v50
	v_add_f32_e32 v64, v64, v51
	v_add_f32_e32 v172, v172, v52
	v_add_f32_e32 v173, v173, v53
	v_add_f32_e32 v177, v177, v54
	v_add_f32_e32 v64, v64, v55
	v_add_f32_e32 v172, v172, v56
	v_add_f32_e32 v173, v173, v57
	v_add_f32_e32 v177, v177, v58
	v_add_f32_e32 v64, v64, v59
	v_add_f32_e32 v172, v172, v60
	v_add_f32_e32 v173, v173, v61
	v_add_f32_e32 v177, v177, v62
	v_add_f32_e32 v64, v64, v63
	v_add_f32_e32 v172, v172, v173
	v_add_f32_e32 v177, v177, v64
	v_add_f32_e32 v172, v172, v177
	v_add_f32_e32 v157, v157, v172
	s_mov_b32 s14, 0x41000000
	s_mov_b32 s15, 0
	v_mfma_f32_32x32x16_bf16 v[16:31], v[202:205], v[234:237], v[16:31]
	v_mfma_f32_32x32x16_bf16 v[0:15], v[218:221], v[234:237], v[0:15]
	v_mfma_f32_32x32x16_bf16 v[16:31], v[206:209], v[238:241], v[16:31]
	v_mfma_f32_32x32x16_bf16 v[0:15], v[222:225], v[238:241], v[0:15]
	v_mfma_f32_32x32x16_bf16 v[16:31], v[210:213], v[242:245], v[16:31]
	v_mfma_f32_32x32x16_bf16 v[0:15], v[226:229], v[242:245], v[0:15]
	v_mfma_f32_32x32x16_bf16 v[16:31], v[214:217], v[246:249], v[16:31]
	v_mfma_f32_32x32x16_bf16 v[0:15], v[230:233], v[246:249], v[0:15]
	s_setprio 0
